# chain loop: S2 B-fragment LDS reads all issued up front into dead quads; bottom-of-loop vmcnt(0) -> vmcnt(16) (only the chunk's 16 stores stay in flight); on top of v13
# speedup vs baseline: 1.0319x; 1.0076x over previous
.LBB0_1181:
	ds_read_b128 v[88:91], v176
	ds_read_b128 v[92:95], v176 offset:64
	v_mov_b64_e32 v[106:107], v[2:3]
	v_mov_b64_e32 v[104:105], v[0:1]
	v_mov_b64_e32 v[122:123], v[6:7]
	s_waitcnt lgkmcnt(1)
	v_mfma_f32_16x16x32_bf16 v[96:99], v[40:43], v[88:91], 0
	v_mov_b64_e32 v[120:121], v[4:5]
	s_ashr_i32 s31, s30, 31
	s_lshl_b64 s[0:1], s[30:31], 14
	v_mfma_f32_16x16x32_bf16 v[88:91], v[48:51], v[88:91], 0
	s_and_b32 s27, s25, 0x1000
	s_add_u32 s0, s7, s0
	s_addc_u32 s1, s19, s1
	s_waitcnt lgkmcnt(0)
	v_mfma_f32_16x16x32_bf16 v[96:99], v[28:31], v[92:95], v[96:99]
	v_lshlrev_b32_e32 v130, 1, v175
	v_mov_b32_e32 v244, v139
	v_mov_b32_e32 v139, v131
	v_mfma_f32_16x16x32_bf16 v[88:91], v[24:27], v[92:95], v[88:91]
	ds_read_b128 v[92:95], v176 offset:128
	ds_read_b128 v[100:103], v176 offset:192
	ds_read_b128 v[0:3], v176 offset:4416
	s_ashr_i32 s29, s28, 31
	s_waitcnt lgkmcnt(2)
	v_mfma_f32_16x16x32_bf16 v[96:99], v[20:23], v[92:95], v[96:99]
	v_mov_b32_e32 v243, v193
	v_mov_b32_e32 v245, v192
	v_add_u32_e32 v209, s23, v205
	v_mfma_f32_16x16x32_bf16 v[88:91], v[16:19], v[92:95], v[88:91]
	ds_read_b128 v[92:95], v176 offset:4352
	v_mov_b32_e32 v242, v194
	s_waitcnt lgkmcnt(2)
	v_mfma_f32_16x16x32_bf16 v[108:111], v[12:15], v[100:103], v[88:91]
	s_waitcnt lgkmcnt(0)
	v_mfma_f32_16x16x32_bf16 v[88:91], v[40:43], v[92:95], 0
	v_mfma_f32_16x16x32_bf16 v[92:95], v[48:51], v[92:95], 0
	v_mfma_f32_16x16x32_bf16 v[124:127], v[8:11], v[100:103], v[96:99]
	ds_read_b128 v[4:7], v176 offset:4480
	s_nop 1
	ds_read_b128 v[96:99], v176 offset:4544
	ds_read_b128 v[100:103], v176 offset:8704
	ds_read_b128 v[116:119], v176 offset:8768
	ds_read_b128 v[210:213], v176 offset:8832
	ds_read_b128 v[214:217], v176 offset:8896
	ds_read_b128 v[218:221], v176 offset:13056
	ds_read_b128 v[222:225], v176 offset:13120
	ds_read_b128 v[226:229], v176 offset:13184
	ds_read_b128 v[230:233], v176 offset:13248
	v_mfma_f32_16x16x32_bf16 v[88:91], v[28:31], v[0:3], v[88:91]
	v_mfma_f32_16x16x32_bf16 v[0:3], v[24:27], v[0:3], v[92:95]
	s_waitcnt lgkmcnt(9)
	v_mfma_f32_16x16x32_bf16 v[0:3], v[16:19], v[4:7], v[0:3]
	s_nop 0
	v_lshl_add_u64 v[92:93], s[0:1], 0, v[142:143]
	v_mfma_f32_16x16x32_bf16 v[88:91], v[20:23], v[4:7], v[88:91]
	v_lshl_add_u64 v[4:5], v[92:93], 0, v[130:131]
	v_lshl_add_u64 v[4:5], v[4:5], 0, v[138:139]
	s_waitcnt lgkmcnt(8)
	v_mfma_f32_16x16x32_bf16 v[112:115], v[12:15], v[96:99], v[0:3]
	s_waitcnt lgkmcnt(7)
	v_mfma_f32_16x16x32_bf16 v[0:3], v[40:43], v[100:103], 0
	v_mfma_f32_16x16x32_bf16 v[234:237], v[8:11], v[96:99], v[88:91]
	s_nop 2
	v_add_u32_e32 v90, s27, v174
	s_waitcnt lgkmcnt(6)
	v_mfma_f32_16x16x32_bf16 v[0:3], v[28:31], v[116:119], v[0:3]
	v_readfirstlane_b32 s27, v90
	s_mov_b32 m0, s27
	v_add_u32_e32 v91, 0x800, v90
	global_load_lds_dwordx4 v[4:5], off
	v_add_u32_e32 v4, s23, v208
	v_ashrrev_i32_e32 v5, 31, v4
	v_lshlrev_b64 v[88:89], 13, v[4:5]
	v_readfirstlane_b32 s27, v91
	v_lshl_add_u64 v[88:89], v[140:141], 0, v[88:89]
	s_mov_b32 m0, s27
	v_add_u32_e32 v91, 0x400, v90
	global_load_lds_dwordx4 v[88:89], off
	v_lshl_add_u64 v[88:89], s[0:1], 0, v[144:145]
	s_waitcnt lgkmcnt(0)
	v_mfma_f32_16x16x32_bf16 v[0:3], v[20:23], v[210:213], v[0:3]
	v_lshl_add_u64 v[88:89], v[88:89], 0, v[130:131]
	v_readfirstlane_b32 s0, v91
	v_lshl_add_u64 v[88:89], v[88:89], 0, v[138:139]
	s_mov_b32 m0, s0
	v_mfma_f32_16x16x32_bf16 v[238:241], v[8:11], v[214:217], v[0:3]
	global_load_lds_dwordx4 v[88:89], off
	v_add_u32_e32 v88, s23, v207
	v_ashrrev_i32_e32 v89, 31, v88
	v_add_u32_e32 v2, 0xc00, v90
	v_mfma_f32_16x16x32_bf16 v[4:7], v[48:51], v[100:103], 0
	v_lshlrev_b64 v[88:89], 13, v[88:89]
	v_readfirstlane_b32 s0, v2
	v_lshl_add_u64 v[0:1], v[140:141], 0, v[88:89]
	s_mov_b32 m0, s0
	v_mfma_f32_16x16x32_bf16 v[4:7], v[24:27], v[116:119], v[4:7]
	global_load_lds_dwordx4 v[0:1], off
	s_ashr_i32 s27, s26, 31
	v_mfma_f32_16x16x32_bf16 v[0:3], v[40:43], v[218:221], 0
	s_lshl_b64 s[0:1], s[28:29], 13
	s_lshl_b64 s[48:49], s[26:27], 14
	v_mfma_f32_16x16x32_bf16 v[40:43], v[48:51], v[218:221], 0
	v_lshl_add_u64 v[48:49], v[150:151], 0, s[48:49]
	v_add_u32_e32 v220, 0x82, v209
	v_ashrrev_i32_e32 v221, 31, v220
	v_mfma_f32_16x16x32_bf16 v[28:31], v[28:31], v[222:225], v[0:3]
	v_lshlrev_b64 v[220:221], 7, v[220:221]
	v_lshl_add_u64 v[220:221], s[14:15], 0, v[220:221]
	v_mfma_f32_16x16x32_bf16 v[24:27], v[24:27], v[222:225], v[40:43]
	v_add_u32_e32 v222, 0x83, v209
	v_ashrrev_i32_e32 v223, 31, v222
	v_lshlrev_b64 v[222:223], 7, v[222:223]
	v_mfma_f32_16x16x32_bf16 v[4:7], v[16:19], v[210:213], v[4:7]
	v_lshl_add_u64 v[222:223], s[14:15], 0, v[222:223]
	v_mfma_f32_16x16x32_bf16 v[20:23], v[20:23], v[226:229], v[28:31]
	s_nop 2
	v_add_u32_e32 v28, s23, v206
	v_mfma_f32_16x16x32_bf16 v[16:19], v[16:19], v[226:229], v[24:27]
	v_ashrrev_i32_e32 v29, 31, v28
	v_lshlrev_b64 v[28:29], 12, v[28:29]
	v_lshl_add_u64 v[210:211], v[154:155], 0, v[28:29]
	v_mfma_f32_16x16x32_bf16 v[116:119], v[12:15], v[214:217], v[4:7]
	v_mul_f32_e32 v229, 0x3fb8aa3b, v243
	v_exp_f32_e32 v229, v229
	s_nop 0
	v_lshl_add_u64 v[4:5], v[148:149], 0, s[0:1]
	s_lshl_b64 s[0:1], s[28:29], 14
	v_lshl_add_u64 v[192:193], v[152:153], 0, s[0:1]
	global_load_dwordx4 v[0:3], v[4:5], off
	s_nop 0
	global_load_dwordx4 v[4:7], v[4:5], off offset:64
	s_nop 0
	global_load_dwordx4 v[100:103], v[48:49], off
	global_load_dwordx4 v[96:99], v[48:49], off offset:64
	global_load_dwordx4 v[92:95], v[48:49], off offset:2048
	global_load_dwordx4 v[88:91], v[48:49], off offset:2112
	global_load_dwordx4 v[40:43], v[192:193], off
	global_load_dwordx4 v[28:31], v[192:193], off offset:64
	v_mfma_f32_16x16x32_bf16 v[212:215], v[8:11], v[230:233], v[20:23]
	global_load_dwordx4 v[48:51], v[210:211], off
	global_load_dwordx4 v[24:27], v[210:211], off offset:64
	s_nop 0
	global_load_dwordx4 v[20:23], v[192:193], off offset:128
	global_load_dwordx4 v[8:11], v[192:193], off offset:192
	v_add_u32_e32 v192, 0x80, v209
	v_ashrrev_i32_e32 v193, 31, v192
	v_mfma_f32_16x16x32_bf16 v[216:219], v[12:15], v[230:233], v[16:19]
	s_nop 2
	global_load_dwordx4 v[16:19], v[210:211], off offset:128
	global_load_dwordx4 v[12:15], v[210:211], off offset:192
	v_add_u32_e32 v210, 0x81, v209
	v_ashrrev_i32_e32 v211, 31, v210
	v_lshlrev_b64 v[192:193], 7, v[192:193]
	v_lshlrev_b64 v[210:211], 7, v[210:211]
	s_add_i32 s0, s25, 0xfffff000
	v_lshl_add_u64 v[192:193], s[14:15], 0, v[192:193]
	v_lshl_add_u64 v[210:211], s[14:15], 0, v[210:211]
	s_and_b32 s0, s0, 0x1000
	global_load_dword v194, v[192:193], off
	s_nop 0
	global_load_dword v193, v[210:211], off
	global_load_dword v139, v[220:221], off
	global_load_dword v192, v[222:223], off
	global_load_dword v130, v131, s[34:35]
	v_add_u32_e32 v210, s0, v174
	v_add_u32_e32 v211, v210, v195
	v_add3_u32 v211, v211, v196, v197
	ds_read2st64_b64 v[220:223], v211 offset1:1
	ds_read2st64_b64 v[224:227], v211 offset0:2 offset1:3
	v_mul_f32_e32 v211, 0x3fb8aa3b, v242
	v_sub_f32_e32 v230, v204, v243
	v_exp_f32_e32 v228, v211
	s_waitcnt lgkmcnt(0)
	v_lshlrev_b32_e32 v243, 16, v220
	v_sub_f32_e32 v211, v204, v242
	v_mul_f32_e32 v230, 0x3fb8aa3b, v230
	v_sub_f32_e32 v243, v243, v124
	v_and_b32_e32 v124, 0xffff0000, v220
	v_mul_f32_e32 v211, 0x3fb8aa3b, v211
	v_exp_f32_e32 v232, v230
	v_mul_f32_e32 v230, 0x3fb8aa3b, v244
	v_sub_f32_e32 v231, v204, v244
	v_sub_f32_e32 v242, v204, v245
	v_sub_f32_e32 v244, v124, v125
	v_alignbit_b32 v124, v221, v220, 16
	v_exp_f32_e32 v211, v211
	v_mul_f32_e32 v231, 0x3fb8aa3b, v231
	v_mul_f32_e32 v242, 0x3fb8aa3b, v242
	v_and_b32_e32 v124, 0xffff0000, v124
	v_exp_f32_e32 v233, v231
	v_exp_f32_e32 v242, v242
	v_sub_f32_e32 v126, v124, v126
	v_and_b32_e32 v124, 0xffff0000, v221
	v_sub_f32_e32 v127, v124, v127
	v_cvt_pk_bf16_f32 v124, v243, v244
	v_cvt_pk_bf16_f32 v125, v126, v127
	ds_write_b64 v178, v[124:125] offset:34816
	v_mul_f32_e32 v124, v211, v243
	v_mul_f32_e32 v125, v232, v244
	v_cvt_pk_bf16_f32 v124, v124, v125
	v_mul_f32_e32 v125, v233, v126
	v_mul_f32_e32 v126, v242, v127
	v_cvt_pk_bf16_f32 v125, v125, v126
	ds_write_b64 v178, v[124:125] offset:53248
	v_lshlrev_b32_e32 v124, 16, v222
	v_sub_f32_e32 v126, v124, v234
	v_and_b32_e32 v124, 0xffff0000, v222
	v_sub_f32_e32 v127, v124, v235
	v_alignbit_b32 v124, v223, v222, 16
	v_and_b32_e32 v124, 0xffff0000, v124
	v_sub_f32_e32 v220, v124, v236
	v_and_b32_e32 v124, 0xffff0000, v223
	v_sub_f32_e32 v221, v124, v237
	v_cvt_pk_bf16_f32 v124, v126, v127
	v_cvt_pk_bf16_f32 v125, v220, v221
	ds_write_b64 v178, v[124:125] offset:37120
	v_mul_f32_e32 v124, v211, v126
	v_mul_f32_e32 v125, v232, v127
	v_cvt_pk_bf16_f32 v124, v124, v125
	v_mul_f32_e32 v125, v233, v220
	v_mul_f32_e32 v126, v242, v221
	v_cvt_pk_bf16_f32 v125, v125, v126
	ds_write_b64 v178, v[124:125] offset:55552
	v_lshlrev_b32_e32 v124, 16, v224
	v_sub_f32_e32 v126, v124, v238
	v_and_b32_e32 v124, 0xffff0000, v224
	v_sub_f32_e32 v127, v124, v239
	v_alignbit_b32 v124, v225, v224, 16
	v_and_b32_e32 v124, 0xffff0000, v124
	v_sub_f32_e32 v220, v124, v240
	v_and_b32_e32 v124, 0xffff0000, v225
	v_sub_f32_e32 v221, v124, v241
	v_cvt_pk_bf16_f32 v124, v126, v127
	v_cvt_pk_bf16_f32 v125, v220, v221
	ds_write_b64 v178, v[124:125] offset:39424
	v_mul_f32_e32 v124, v211, v126
	v_mul_f32_e32 v125, v232, v127
	v_cvt_pk_bf16_f32 v124, v124, v125
	v_mul_f32_e32 v125, v233, v220
	v_mul_f32_e32 v126, v242, v221
	v_cvt_pk_bf16_f32 v125, v125, v126
	ds_write_b64 v178, v[124:125] offset:57856
	v_lshlrev_b32_e32 v124, 16, v226
	v_sub_f32_e32 v126, v124, v212
	v_and_b32_e32 v124, 0xffff0000, v226
	v_sub_f32_e32 v127, v124, v213
	v_alignbit_b32 v124, v227, v226, 16
	v_and_b32_e32 v124, 0xffff0000, v124
	v_sub_f32_e32 v212, v124, v214
	v_and_b32_e32 v124, 0xffff0000, v227
	v_sub_f32_e32 v213, v124, v215
	v_cvt_pk_bf16_f32 v124, v126, v127
	v_cvt_pk_bf16_f32 v125, v212, v213
	ds_write_b64 v178, v[124:125] offset:41728
	v_mul_f32_e32 v124, v211, v126
	v_mul_f32_e32 v125, v232, v127
	v_cvt_pk_bf16_f32 v124, v124, v125
	v_mul_f32_e32 v125, v233, v212
	v_mul_f32_e32 v126, v242, v213
	v_cvt_pk_bf16_f32 v125, v125, v126
	ds_write_b64 v178, v[124:125] offset:60160
	v_mul_f32_e32 v231, 0x3fb8aa3b, v245
	s_waitcnt lgkmcnt(0)
	s_barrier
	v_exp_f32_e32 v230, v230
	v_exp_f32_e32 v231, v231
	ds_read_b128 v[124:127], v180 offset:34816
	ds_read_b128 v[220:223], v180 offset:34880
	ds_read_b128 v[224:227], v180 offset:37120
	ds_read_b128 v[232:235], v180 offset:37184
	ds_read_b128 v[236:239], v180 offset:39424
	ds_read_b128 v[240:243], v180 offset:39488
	ds_read_b128 v[250:253], v180 offset:41728
	v_mul_f32_e64 v212, v228, v216
	v_mul_f32_e64 v213, v229, v217
	v_pk_mul_f32 v[214:215], v[230:231], v[218:219]
	ds_read_b128 v[216:219], v180 offset:41792
	v_pk_mul_f32 v[108:109], v[228:229], v[108:109]
	v_pk_mul_f32 v[110:111], v[230:231], v[110:111]
	v_pk_mul_f32 v[112:113], v[228:229], v[112:113]
	v_pk_mul_f32 v[114:115], v[230:231], v[114:115]
	s_waitcnt lgkmcnt(6)
	v_mfma_f32_16x16x32_bf16 v[108:111], v[104:107], v[124:127], v[108:111]
	v_pk_mul_f32 v[116:117], v[228:229], v[116:117]
	v_pk_mul_f32 v[118:119], v[230:231], v[118:119]
	v_mfma_f32_16x16x32_bf16 v[108:111], v[120:123], v[220:223], v[108:111]
	s_waitcnt lgkmcnt(4)
	v_mfma_f32_16x16x32_bf16 v[112:115], v[104:107], v[224:227], v[112:115]
	v_mfma_f32_16x16x32_bf16 v[112:115], v[120:123], v[232:235], v[112:115]
	s_waitcnt lgkmcnt(2)
	v_mfma_f32_16x16x32_bf16 v[116:119], v[104:107], v[236:239], v[116:119]
	v_mfma_f32_16x16x32_bf16 v[116:119], v[120:123], v[240:243], v[116:119]
	s_waitcnt lgkmcnt(0)
	v_mfma_f32_16x16x32_bf16 v[104:107], v[104:107], v[250:253], v[212:215]
	v_mfma_f32_16x16x32_bf16 v[104:107], v[120:123], v[216:219], v[104:107]
	v_mul_f32_e64 v120, v114, v114
	v_mul_f32_e64 v121, v115, v115
	v_pk_mul_f32 v[122:123], v[112:113], v[112:113]
	v_pk_fma_f32 v[120:121], v[110:111], v[110:111], v[120:121]
	v_pk_fma_f32 v[122:123], v[108:109], v[108:109], v[122:123]
	v_pk_fma_f32 v[120:121], v[118:119], v[118:119], v[120:121]
	v_pk_fma_f32 v[122:123], v[116:117], v[116:117], v[122:123]
	s_nop 0
	v_pk_fma_f32 v[120:121], v[106:107], v[106:107], v[120:121]
	v_pk_fma_f32 v[122:123], v[104:105], v[104:105], v[122:123]
	s_nop 1
	v_add_f32_dpp v120, v120, v120 quad_perm:[1,0,3,2] row_mask:0xf bank_mask:0xf
	v_add_f32_dpp v121, v121, v121 quad_perm:[1,0,3,2] row_mask:0xf bank_mask:0xf
	v_add_f32_dpp v122, v122, v122 quad_perm:[1,0,3,2] row_mask:0xf bank_mask:0xf
	v_add_f32_dpp v123, v123, v123 quad_perm:[1,0,3,2] row_mask:0xf bank_mask:0xf
	v_add_f32_dpp v120, v120, v120 quad_perm:[2,3,0,1] row_mask:0xf bank_mask:0xf
	v_add_f32_dpp v121, v121, v121 quad_perm:[2,3,0,1] row_mask:0xf bank_mask:0xf
	v_add_f32_dpp v122, v122, v122 quad_perm:[2,3,0,1] row_mask:0xf bank_mask:0xf
	v_add_f32_dpp v123, v123, v123 quad_perm:[2,3,0,1] row_mask:0xf bank_mask:0xf
	v_add_f32_dpp v120, v120, v120 row_ror:12 row_mask:0xf bank_mask:0xf
	v_add_f32_dpp v121, v121, v121 row_ror:12 row_mask:0xf bank_mask:0xf
	v_add_f32_dpp v122, v122, v122 row_ror:12 row_mask:0xf bank_mask:0xf
	v_add_f32_dpp v123, v123, v123 row_ror:12 row_mask:0xf bank_mask:0xf
	v_add_f32_dpp v120, v120, v120 row_ror:8 row_mask:0xf bank_mask:0xf
	v_add_f32_dpp v121, v121, v121 row_ror:8 row_mask:0xf bank_mask:0xf
	v_add_f32_dpp v122, v122, v122 row_ror:8 row_mask:0xf bank_mask:0xf
	v_add_f32_dpp v123, v123, v123 row_ror:8 row_mask:0xf bank_mask:0xf
	s_and_saveexec_b64 s[0:1], vcc
	s_cbranch_execz .LBB0_1183
	ds_write2_b32 v198, v122, v123 offset1:1
	ds_write2_b32 v198, v120, v121 offset0:2 offset1:3
.LBB0_1183:
	s_or_b64 exec, exec, s[0:1]
	v_mul_f32_e32 v120, 0x3fb8aa3b, v204
	v_exp_f32_e32 v204, v120
	s_waitcnt lgkmcnt(0)
	ds_read_b128 v[120:123], v188 offset:53248
	ds_read_b128 v[124:127], v188 offset:53312
	ds_read_b128 v[212:215], v191 offset:53248
	ds_read_b128 v[216:219], v191 offset:53312
	ds_read_b128 v[220:223], v189 offset:53248
	ds_read_b128 v[224:227], v189 offset:53312
	v_pk_mul_f32 v[54:55], v[54:55], v[204:205] op_sel_hi:[1,0]
	v_pk_mul_f32 v[52:53], v[52:53], v[204:205] op_sel_hi:[1,0]
	v_pk_mul_f32 v[58:59], v[58:59], v[204:205] op_sel_hi:[1,0]
	v_pk_mul_f32 v[56:57], v[56:57], v[204:205] op_sel_hi:[1,0]
	s_waitcnt lgkmcnt(0)
	v_mfma_f32_16x16x32_bf16 v[52:55], v[80:83], v[120:123], v[52:55]
	v_mul_f32_e64 v46, v46, v204
	v_mul_f32_e64 v47, v47, v204
	v_pk_mul_f32 v[44:45], v[44:45], v[204:205] op_sel_hi:[1,0]
	v_pk_mul_f32 v[38:39], v[38:39], v[204:205] op_sel_hi:[1,0]
	v_pk_mul_f32 v[36:37], v[36:37], v[204:205] op_sel_hi:[1,0]
	ds_read_b128 v[228:231], v187 offset:53248
	ds_read_b128 v[232:235], v187 offset:53312
	v_add_u32_e32 v255, v210, v199
	v_add3_u32 v255, v255, v200, v201
	ds_read_u16 v236, v255 offset:2048
	ds_read_u16 v237, v255 offset:2080
	ds_read_u16 v238, v255 offset:2112
	ds_read_u16 v239, v255 offset:2144
	ds_read_u16 v240, v255 offset:2176
	ds_read_u16 v241, v255 offset:2208
	ds_read_u16 v242, v255 offset:2240
	ds_read_u16 v243, v255 offset:2272
	ds_read_u16 v244, v255 offset:2304
	ds_read_u16 v245, v255 offset:2336
	ds_read_u16 v249, v255 offset:2368
	ds_read_u16 v250, v255 offset:2400
	ds_read_u16 v251, v255 offset:2432
	ds_read_u16 v252, v255 offset:2464
	ds_read_u16 v253, v255 offset:2496
	ds_read_u16 v254, v255 offset:2528
	v_pk_mul_f32 v[62:63], v[62:63], v[204:205] op_sel_hi:[1,0]
	v_pk_mul_f32 v[60:61], v[60:61], v[204:205] op_sel_hi:[1,0]
	v_pk_mul_f32 v[66:67], v[66:67], v[204:205] op_sel_hi:[1,0]
	v_pk_mul_f32 v[64:65], v[64:65], v[204:205] op_sel_hi:[1,0]
	v_mfma_f32_16x16x32_bf16 v[56:59], v[72:75], v[120:123], v[56:59]
	v_mul_f32_e64 v34, v34, v204
	v_mul_f32_e64 v35, v35, v204
	v_pk_mul_f32 v[32:33], v[32:33], v[204:205] op_sel_hi:[1,0]
	v_pk_mul_f32 v[70:71], v[70:71], v[204:205] op_sel_hi:[1,0]
	v_mfma_f32_16x16x32_bf16 v[44:47], v[80:83], v[212:215], v[44:47]
	v_mul_f32_e64 v68, v68, v204
	v_mul_f32_e64 v69, v69, v204
	s_waitcnt lgkmcnt(0)
	s_barrier
	v_mfma_f32_16x16x32_bf16 v[36:39], v[80:83], v[220:223], v[36:39]
	v_lshlrev_b32_e32 v236, 16, v236
	v_lshlrev_b32_e32 v237, 16, v237
	v_lshlrev_b32_e32 v238, 16, v238
	v_lshlrev_b32_e32 v239, 16, v239
	v_lshlrev_b32_e32 v240, 16, v240
	v_lshlrev_b32_e32 v241, 16, v241
	v_lshlrev_b32_e32 v242, 16, v242
	v_lshlrev_b32_e32 v243, 16, v243
	s_add_i32 s23, s23, 64
	s_addk_i32 s25, 0x1000
	v_mfma_f32_16x16x32_bf16 v[60:63], v[72:75], v[212:215], v[60:63]
	v_lshlrev_b32_e32 v244, 16, v244
	v_lshlrev_b32_e32 v245, 16, v245
	v_lshlrev_b32_e32 v249, 16, v249
	v_lshlrev_b32_e32 v250, 16, v250
	v_lshlrev_b32_e32 v251, 16, v251
	v_lshlrev_b32_e32 v252, 16, v252
	v_lshlrev_b32_e32 v253, 16, v253
	v_lshlrev_b32_e32 v254, 16, v254
	s_add_i32 s30, s30, 32
	s_add_i32 s26, s26, 16
	s_add_i32 s28, s28, 32
	v_mfma_f32_16x16x32_bf16 v[64:67], v[72:75], v[220:223], v[64:67]
	s_add_u32 s34, s34, 0x2000
	s_addc_u32 s35, s35, 0
	s_cmpk_eq_i32 s23, 0x780
	v_mfma_f32_16x16x32_bf16 v[52:55], v[84:87], v[124:127], v[52:55]
	v_mul_f32_e32 v212, 0xbfb8aa3b, v236
	v_mul_f32_e32 v213, 0xbfb8aa3b, v237
	v_mul_f32_e32 v214, 0xbfb8aa3b, v238
	v_mul_f32_e32 v215, 0xbfb8aa3b, v239
	v_mul_f32_e32 v220, 0xbfb8aa3b, v240
	v_mul_f32_e32 v221, 0xbfb8aa3b, v241
	v_mul_f32_e32 v222, 0xbfb8aa3b, v242
	v_mul_f32_e32 v223, 0xbfb8aa3b, v243
	v_mfma_f32_16x16x32_bf16 v[56:59], v[76:79], v[124:127], v[56:59]
	v_exp_f32_e32 v212, v212
	v_exp_f32_e32 v213, v213
	v_exp_f32_e32 v214, v214
	v_exp_f32_e32 v215, v215
	v_exp_f32_e32 v220, v220
	v_exp_f32_e32 v221, v221
	v_exp_f32_e32 v222, v222
	v_exp_f32_e32 v223, v223
	v_mfma_f32_16x16x32_bf16 v[44:47], v[84:87], v[216:219], v[44:47]
	v_add_f32_e32 v212, 1.0, v212
	v_add_f32_e32 v213, 1.0, v213
	v_add_f32_e32 v214, 1.0, v214
	v_add_f32_e32 v215, 1.0, v215
	v_add_f32_e32 v220, 1.0, v220
	v_add_f32_e32 v221, 1.0, v221
	v_add_f32_e32 v222, 1.0, v222
	v_add_f32_e32 v223, 1.0, v223
	v_mfma_f32_16x16x32_bf16 v[36:39], v[84:87], v[224:227], v[36:39]
	v_rcp_f32_e32 v212, v212
	v_rcp_f32_e32 v213, v213
	v_rcp_f32_e32 v214, v214
	v_rcp_f32_e32 v215, v215
	v_rcp_f32_e32 v220, v220
	v_rcp_f32_e32 v221, v221
	v_rcp_f32_e32 v222, v222
	v_rcp_f32_e32 v223, v223
	s_nop 5
	v_cvt_pk_bf16_f32 v120, v56, v57
	v_cvt_pk_bf16_f32 v121, v58, v59
	s_waitcnt lgkmcnt(0)
	v_mfma_f32_16x16x32_bf16 v[32:35], v[80:83], v[228:231], v[32:35]
	v_mul_f32_e32 v236, v212, v236
	v_mul_f32_e32 v237, v213, v237
	v_mul_f32_e32 v238, v214, v238
	v_mul_f32_e32 v239, v215, v239
	v_mul_f32_e32 v240, v220, v240
	v_mul_f32_e32 v241, v221, v241
	v_mul_f32_e32 v242, v222, v242
	v_mul_f32_e32 v243, v223, v243
	v_cvt_pk_bf16_f32 v80, v52, v53
	v_cvt_pk_bf16_f32 v81, v54, v55
	v_cvt_pk_bf16_f32 v82, v44, v45
	v_mfma_f32_16x16x32_bf16 v[60:63], v[76:79], v[216:219], v[60:63]
	v_mul_f32_e32 v212, 0xbfb8aa3b, v244
	v_mul_f32_e32 v213, 0xbfb8aa3b, v245
	v_mul_f32_e32 v214, 0xbfb8aa3b, v249
	v_mul_f32_e32 v215, 0xbfb8aa3b, v250
	v_mul_f32_e32 v220, 0xbfb8aa3b, v251
	v_mul_f32_e32 v221, 0xbfb8aa3b, v252
	v_mul_f32_e32 v222, 0xbfb8aa3b, v253
	v_mul_f32_e32 v223, 0xbfb8aa3b, v254
	v_cvt_pk_bf16_f32 v83, v46, v47
	ds_write2_b64 v173, v[80:81], v[120:121] offset1:4
	v_mfma_f32_16x16x32_bf16 v[64:67], v[76:79], v[224:227], v[64:67]
	v_exp_f32_e32 v212, v212
	v_exp_f32_e32 v213, v213
	v_exp_f32_e32 v214, v214
	v_exp_f32_e32 v215, v215
	v_exp_f32_e32 v220, v220
	v_exp_f32_e32 v221, v221
	v_exp_f32_e32 v222, v222
	v_exp_f32_e32 v223, v223
	v_mfma_f32_16x16x32_bf16 v[68:71], v[72:75], v[228:231], v[68:71]
	v_add_f32_e32 v212, 1.0, v212
	v_add_f32_e32 v213, 1.0, v213
	v_add_f32_e32 v214, 1.0, v214
	v_add_f32_e32 v215, 1.0, v215
	v_add_f32_e32 v220, 1.0, v220
	v_add_f32_e32 v221, 1.0, v221
	v_add_f32_e32 v222, 1.0, v222
	v_add_f32_e32 v223, 1.0, v223
	s_nop 3
	v_cvt_pk_bf16_f32 v80, v60, v61
	v_cvt_pk_bf16_f32 v81, v62, v63
	s_nop 0
	v_cvt_pk_bf16_f32 v72, v64, v65
	v_mfma_f32_16x16x32_bf16 v[32:35], v[84:87], v[232:235], v[32:35]
	v_rcp_f32_e32 v212, v212
	v_rcp_f32_e32 v213, v213
	v_rcp_f32_e32 v214, v214
	v_rcp_f32_e32 v215, v215
	v_rcp_f32_e32 v220, v220
	v_rcp_f32_e32 v221, v221
	v_rcp_f32_e32 v222, v222
	v_rcp_f32_e32 v223, v223
	v_cvt_pk_bf16_f32 v84, v36, v37
	v_cvt_pk_bf16_f32 v85, v38, v39
	v_cvt_pk_bf16_f32 v73, v66, v67
	v_mfma_f32_16x16x32_bf16 v[68:71], v[76:79], v[232:235], v[68:71]
	v_mul_f32_e32 v244, v212, v244
	v_mul_f32_e32 v245, v213, v245
	v_mul_f32_e32 v249, v214, v249
	v_mul_f32_e32 v250, v215, v250
	v_mul_f32_e32 v251, v220, v251
	v_mul_f32_e32 v252, v221, v252
	v_mul_f32_e32 v253, v222, v253
	v_mul_f32_e32 v254, v223, v254
	ds_write2_b64 v184, v[82:83], v[80:81] offset0:32 offset1:36
	ds_write2_b64 v185, v[84:85], v[72:73] offset0:64 offset1:68
	v_cvt_pk_bf16_f32 v86, v32, v33
	v_cvt_pk_bf16_f32 v87, v34, v35
	v_cvt_pk_bf16_f32 v72, v68, v69
	v_cvt_pk_bf16_f32 v73, v70, v71
	ds_write2_b64 v186, v[86:87], v[72:73] offset0:96 offset1:100
	ds_read_b128 v[72:75], v179
	ds_read_b128 v[76:79], v179 offset:256
	v_add_u32_e32 v80, 64, v209
	v_ashrrev_i32_e32 v81, 31, v80
	v_lshlrev_b64 v[80:81], 13, v[80:81]
	v_lshl_add_u64 v[80:81], v[156:157], 0, v[80:81]
	v_add_u32_e32 v82, 0x41, v209
	v_ashrrev_i32_e32 v83, 31, v82
	v_lshlrev_b64 v[82:83], 13, v[82:83]
	v_lshl_add_u64 v[82:83], v[156:157], 0, v[82:83]
	v_add_u32_e32 v84, 0x42, v209
	v_ashrrev_i32_e32 v85, 31, v84
	v_lshlrev_b64 v[84:85], 13, v[84:85]
	v_lshl_add_u64 v[84:85], v[156:157], 0, v[84:85]
	v_add_u32_e32 v86, 0x43, v209
	v_ashrrev_i32_e32 v87, 31, v86
	v_lshlrev_b64 v[86:87], 13, v[86:87]
	v_lshl_add_u64 v[86:87], v[156:157], 0, v[86:87]
	s_waitcnt lgkmcnt(0)
	v_pk_add_f32 v[72:73], v[72:73], v[76:77]
	v_pk_add_f32 v[74:75], v[74:75], v[78:79]
	v_mov_b64_e32 v[76:77], s[20:21]
	v_pk_fma_f32 v[72:73], v[72:73], s[18:19], v[76:77] op_sel_hi:[1,0,0]
	v_pk_fma_f32 v[74:75], v[74:75], s[18:19], v[76:77] op_sel_hi:[1,0,0]
	v_cmp_gt_f32_e64 s[0:1], s45, v72
	v_cmp_gt_f32_e64 s[98:99], s45, v73
	v_cmp_gt_f32_e64 s[100:101], s45, v74
	v_mul_f32_e32 v120, 0x4b800000, v72
	v_mul_f32_e32 v121, 0x4b800000, v73
	v_mul_f32_e32 v122, 0x4b800000, v74
	v_mul_f32_e32 v123, 0x4b800000, v75
	v_cndmask_b32_e64 v72, v72, v120, s[0:1]
	v_cndmask_b32_e64 v73, v73, v121, s[98:99]
	v_cndmask_b32_e64 v74, v74, v122, s[100:101]
	v_rsq_f32_e32 v72, v72
	v_rsq_f32_e32 v73, v73
	v_rsq_f32_e32 v74, v74
	s_nop 0
	v_mul_f32_e32 v120, 0x45800000, v72
	v_mul_f32_e32 v121, 0x45800000, v73
	v_mul_f32_e32 v122, 0x45800000, v74
	v_cndmask_b32_e64 v72, v72, v120, s[0:1]
	v_cndmask_b32_e64 v73, v73, v121, s[98:99]
	v_cndmask_b32_e64 v74, v74, v122, s[100:101]
	v_cmp_gt_f32_e64 s[0:1], s45, v75
	s_nop 0
	v_cndmask_b32_e64 v75, v75, v123, s[0:1]
	v_rsq_f32_e32 v75, v75
	v_mul_f32_e32 v120, v108, v72
	v_mul_f32_e32 v121, v112, v72
	v_mul_f32_e32 v122, v116, v72
	v_mul_f32_e32 v123, v104, v72
	v_mul_f32_e32 v120, v172, v120
	v_mul_f32_e32 v121, v171, v121
	v_mul_f32_e32 v122, v170, v122
	v_mul_f32_e32 v123, v169, v123
	v_mul_f32_e32 v120, v236, v120
	v_mul_f32_e32 v121, v237, v121
	v_mul_f32_e32 v122, v238, v122
	v_mul_f32_e32 v123, v239, v123
	v_cvt_pk_bf16_f32 v120, v120, s0
	v_cvt_pk_bf16_f32 v121, v121, s0
	v_cvt_pk_bf16_f32 v122, v122, s0
	v_cvt_pk_bf16_f32 v123, v123, s0
	global_store_short v[80:81], v120, off
	global_store_short v[80:81], v121, off offset:32
	global_store_short v[80:81], v122, off offset:64
	global_store_short v[80:81], v123, off offset:96
	v_mul_f32_e32 v124, 0x45800000, v75
	v_cndmask_b32_e64 v75, v75, v124, s[0:1]
	v_mul_f32_e32 v120, v109, v73
	v_mul_f32_e32 v121, v113, v73
	v_mul_f32_e32 v122, v117, v73
	v_mul_f32_e32 v123, v105, v73
	v_mul_f32_e32 v120, v172, v120
	v_mul_f32_e32 v121, v171, v121
	v_mul_f32_e32 v122, v170, v122
	v_mul_f32_e32 v123, v169, v123
	v_mul_f32_e32 v120, v240, v120
	v_mul_f32_e32 v121, v241, v121
	v_mul_f32_e32 v122, v242, v122
	v_mul_f32_e32 v123, v243, v123
	v_cvt_pk_bf16_f32 v120, v120, s0
	v_cvt_pk_bf16_f32 v121, v121, s0
	v_cvt_pk_bf16_f32 v122, v122, s0
	v_cvt_pk_bf16_f32 v123, v123, s0
	global_store_short v[82:83], v120, off
	global_store_short v[82:83], v121, off offset:32
	global_store_short v[82:83], v122, off offset:64
	global_store_short v[82:83], v123, off offset:96
	v_mul_f32_e32 v120, v110, v74
	v_mul_f32_e32 v121, v114, v74
	v_mul_f32_e32 v122, v118, v74
	v_mul_f32_e32 v123, v106, v74
	v_mul_f32_e32 v120, v172, v120
	v_mul_f32_e32 v121, v171, v121
	v_mul_f32_e32 v122, v170, v122
	v_mul_f32_e32 v123, v169, v123
	v_mul_f32_e32 v120, v244, v120
	v_mul_f32_e32 v121, v245, v121
	v_mul_f32_e32 v122, v249, v122
	v_mul_f32_e32 v123, v250, v123
	v_cvt_pk_bf16_f32 v120, v120, s0
	v_cvt_pk_bf16_f32 v121, v121, s0
	v_cvt_pk_bf16_f32 v122, v122, s0
	v_cvt_pk_bf16_f32 v123, v123, s0
	global_store_short v[84:85], v120, off
	global_store_short v[84:85], v121, off offset:32
	global_store_short v[84:85], v122, off offset:64
	global_store_short v[84:85], v123, off offset:96
	v_mul_f32_e32 v120, v111, v75
	v_mul_f32_e32 v121, v115, v75
	v_mul_f32_e32 v122, v119, v75
	v_mul_f32_e32 v123, v107, v75
	v_mul_f32_e32 v120, v172, v120
	v_mul_f32_e32 v121, v171, v121
	v_mul_f32_e32 v122, v170, v122
	v_mul_f32_e32 v123, v169, v123
	v_mul_f32_e32 v120, v251, v120
	v_mul_f32_e32 v121, v252, v121
	v_mul_f32_e32 v122, v253, v122
	v_mul_f32_e32 v123, v254, v123
	v_cvt_pk_bf16_f32 v120, v120, s0
	v_cvt_pk_bf16_f32 v121, v121, s0
	v_cvt_pk_bf16_f32 v122, v122, s0
	v_cvt_pk_bf16_f32 v123, v123, s0
	global_store_short v[86:87], v120, off
	global_store_short v[86:87], v121, off offset:32
	global_store_short v[86:87], v122, off offset:64
	global_store_short v[86:87], v123, off offset:96
	s_waitcnt lgkmcnt(0)
	s_barrier
	s_cbranch_scc1 .LBB0_1185
	s_waitcnt vmcnt(16)
	v_mov_b64_e32 v[76:77], v[88:89]
	v_mov_b64_e32 v[72:73], v[92:93]
	v_mov_b64_e32 v[84:85], v[96:97]
	v_mov_b64_e32 v[80:81], v[100:101]
	v_mov_b64_e32 v[78:79], v[90:91]
	v_mov_b64_e32 v[74:75], v[94:95]
	v_mov_b64_e32 v[86:87], v[98:99]
	v_mov_b64_e32 v[82:83], v[102:103]
	v_mov_b32_e32 v204, v130
	s_branch .LBB0_1181
